# v21 + dead per-score lane-mask precomputation removed from the NSA item pre-loop (62 v_cmp, 52 v_writelane, 48 s_nop per item)
# baseline (speedup 1.0000x reference)
; #define LAS __attribute__((address_space(3)))
; DI f32x16 mma32(bf16x8 a, bf16x8 b, f32x16 c) { return __builtin_amdgcn_mfma_f32_32x32x16_bf16(a, b, c, 0, 0, 0); }
; DI bf16x8 packp(const f32x16& x, const int h8) { v4u p; p.x = pk2(x[h8 + 0], x[h8 + 1]); p.y = pk2(x[h8 + 2], x[h8 + 3]); p.z = pk2(x[h8 + 4], x[h8 + 5]); p.w = pk2(x[h8 + 6], x[h8 + 7]); return __builtin_bit_cast(bf16x8, p); }
; #define NSA_STORE(Kb, Vb) do { *(LAS v4u*)((Kb) + skey * PA + 8 * sch) = kreg; LAS unsigned* d0_ = (LAS unsigned*)((Vb) + (4 * sdg) * PV + vpos(2 * skp)); \
;         d0_[0] = (vr0.x & 0xffffu) | (vr1.x << 16); d0_[PV / 2] = (vr0.x >> 16) | (vr1.x & 0xffff0000u); d0_[PV] = (vr0.y & 0xffffu) | (vr1.y << 16); d0_[3 * PV / 2] = (vr0.y >> 16) | (vr1.y & 0xffff0000u); } while (0)
; DI void nsa_item(KA a, LAS unsigned char* lds, const int it) {
;     ...
;         f32x16 ot[2] = {ZERO16, ZERO16};
; #pragma unroll
;         for (int sp = 0; sp < 8; ++sp) { const bf16x8 pf = packp(st[sp >> 1], 8 * (sp & 1));
; #pragma unroll
;             for (int dh = 0; dh < 2; ++dh) ot[dh] = mma32(vfrag(VT, 32 * dh + r, sp, hf), pf, ot[dh]); }
;         of[0] = ot[0] * g0; of[1] = ot[1] * g0;
;     ...
;     const unsigned mysel = SELM[tql]; const int n = *NLIST;
;     LAS bf16* Kt1 = (LAS bf16*)(lds + NSA_KT1); LAS bf16* VT1 = (LAS bf16*)(lds + NSA_VT1);
;     NSA_STORE(Kt, VT);
;     NSA_LOAD(LIST[1]);
;     __syncthreads();
;     float m_ref = 0.f, l_run = 0.f; f32x16 ot[2] = {ZERO16, ZERO16}; int curtype = 0;
.LBB0_794:
	v_add_f32_e32 v33, 1.0, v33
	v_rcp_f32_e32 v34, v33
	s_andn2_b64 vcc, exec, s[0:1]
	v_readlane_b32 s90, v254, 47
	v_pk_mul_f32 v[124:125], v[34:35], v[30:31] op_sel_hi:[0,1]
	v_pk_mul_f32 v[120:121], v[34:35], v[28:29] op_sel_hi:[0,1]
	v_pk_mul_f32 v[116:117], v[34:35], v[26:27] op_sel_hi:[0,1]
	v_pk_mul_f32 v[112:113], v[34:35], v[24:25] op_sel_hi:[0,1]
	v_pk_mul_f32 v[108:109], v[34:35], v[22:23] op_sel_hi:[0,1]
	v_pk_mul_f32 v[104:105], v[34:35], v[20:21] op_sel_hi:[0,1]
	v_pk_mul_f32 v[100:101], v[34:35], v[18:19] op_sel_hi:[0,1]
	v_pk_mul_f32 v[96:97], v[34:35], v[16:17] op_sel_hi:[0,1]
	v_pk_mul_f32 v[122:123], v[34:35], v[14:15] op_sel_hi:[0,1]
	v_pk_mul_f32 v[118:119], v[34:35], v[12:13] op_sel_hi:[0,1]
	v_pk_mul_f32 v[114:115], v[34:35], v[10:11] op_sel_hi:[0,1]
	v_pk_mul_f32 v[110:111], v[34:35], v[8:9] op_sel_hi:[0,1]
	v_pk_mul_f32 v[106:107], v[34:35], v[6:7] op_sel_hi:[0,1]
	v_pk_mul_f32 v[102:103], v[34:35], v[4:5] op_sel_hi:[0,1]
	v_pk_mul_f32 v[98:99], v[34:35], v[2:3] op_sel_hi:[0,1]
	v_pk_mul_f32 v[94:95], v[34:35], v[0:1] op_sel_hi:[0,1]
	v_mov_b32_e32 v31, 0
	s_cbranch_vccnz .LBB0_811
	s_sub_i32 s85, 23, s40
	s_mov_b32 s87, 0
	s_mov_b32 s88, 0
	v_mov_b32_e32 v137, 0
	v_mov_b32_e32 v16, 0
	v_readlane_b32 s86, v254, 13
	v_mov_b32_e32 v135, 0
	v_mov_b32_e32 v0, 0
	v_mov_b32_e32 v1, v135
	v_mov_b32_e32 v2, v135
	v_mov_b32_e32 v3, v135
	v_mov_b32_e32 v4, v135
	v_mov_b32_e32 v5, v135
	v_mov_b32_e32 v6, v135
	v_mov_b32_e32 v7, v135
	v_mov_b32_e32 v8, v135
	v_mov_b32_e32 v9, v135
	v_mov_b32_e32 v10, v135
	v_mov_b32_e32 v11, v135
	v_mov_b32_e32 v12, v135
	v_mov_b32_e32 v13, v135
	v_mov_b32_e32 v14, v135
	v_mov_b32_e32 v15, v135
	v_mov_b32_e32 v17, v135
	v_mov_b32_e32 v18, v135
	v_mov_b32_e32 v19, v135
	v_mov_b32_e32 v20, v135
	v_mov_b32_e32 v21, v135
	v_mov_b32_e32 v22, v135
	v_mov_b32_e32 v23, v135
	v_mov_b32_e32 v24, v135
	v_mov_b32_e32 v25, v135
	v_mov_b32_e32 v26, v135
	v_mov_b32_e32 v27, v135
	v_mov_b32_e32 v28, v135
	v_mov_b32_e32 v29, v135
	v_mov_b32_e32 v30, v135
	v_mov_b32_e32 v31, v135
	s_movk_i32 s74, 0x1c00
	v_mad_u32_u24 v190, v132, s74, v192
	v_mad_u32_u24 v251, v133, s74, v88
	v_add_u32_e32 v251, 0x100, v251
	v_add_u32_e32 v241, 0x1c00, v251
	v_readlane_b32 s74, v254, 48
	v_readlane_b32 s98, v254, 39
	v_readlane_b32 s99, v254, 40
	s_mov_b32 s100, 0x5040100
	s_mul_i32 s74, s74, 0x1c00
	s_lshl_b32 s75, s33, 1
	s_add_u32 s74, s74, s75
	s_add_u32 s98, s98, s74
	s_addc_u32 s99, s99, 0
	s_mov_b32 s101, 0x7060302
	v_and_b32_e32 v242, 31, v238
	v_lshrrev_b32_e32 v243, 5, v238
	v_lshlrev_b32_e32 v243, 2, v243
	v_sub_u32_e32 v242, v242, v243
	v_bfe_u32 v243, v232, 6, 1
	v_lshl_add_u32 v242, v243, 5, v242
	v_add3_u32 v231, 0, v90, v130
	s_movk_i32 s74, 0x4800
	v_add3_u32 v230, s74, v90, v131
	ds_read_b128 v[170:173], v231 offset:64
	ds_read_b128 v[178:181], v231 offset:4608
	ds_read_b128 v[182:185], v231 offset:4640
	ds_read_b128 v[186:189], v231 offset:4672
	ds_read_b128 v[206:209], v231 offset:4704
	ds_read_b128 v[174:177], v231 offset:96
	s_add_i32 s74, s86, -8
	v_mov_b32_e32 v244, s74
	ds_read_b32 v191, v244
	ds_read_b32 v250, v244 offset:8
	ds_read_b128 v[210:213], v230
	ds_read_b128 v[218:221], v230 offset:8704
	ds_read_b128 v[222:225], v230 offset:8736
	ds_read_b128 v[214:217], v230 offset:32
	ds_read_b128 v[226:229], v230 offset:64
	ds_read_b128 v[152:155], v230 offset:8768
	ds_read_b128 v[246:249], v230 offset:96
	ds_read_b128 v[144:147], v231
	ds_read_b128 v[148:151], v231 offset:32
